# sample attention items: page-table row of the item cached in LDS (loader waves' per-tile page lookup is an LDS read), plus skipped unused lookup; on top of v019
# speedup vs baseline: 1.0040x; 1.0008x over previous
; __device__ __forceinline__ void attn_item(const P& p, Frame& F, const bool is_s, const int b, const int g, const int c) {
;     ...
;     const int* pt = (const int*)p.in[I_PT] + b * NPAGES; const float* ckv = p.in[I_CKV]; const float* cw = p.in[I_CWIN];
;     ...
;                 if (tid2 == 0) { int n = 0; for (int j = 0; j < 129; ++j) { const int msk = SELB[j] | (SELB[132 + j] << 1) | (SELB[264 + j] << 2) | (SELB[396 + j] << 3); if (msk) { UL[n] = j; UM[n] = msk; ++n; } } NU[0] = n; }
.LBB0_1991:
	s_or_b64 exec, exec, s[0:1]
	v_cmp_eq_u32_e32 vcc, 0, v9
	s_waitcnt lgkmcnt(0)
	s_barrier
	s_mov_b64 s[0:1], exec
	v_readfirstlane_b32 s2, v9
	s_mov_b32 s7, 0
	s_nop 2
	s_cmp_lt_u32 s2, 64
	s_cbranch_scc0 .LBB0_2001
	v_lshlrev_b32_e32 v1, 2, v9
	global_load_dword v16, v1, s[76:77]
	v_mov_b32_e32 v8, 0x19600
	v_lshl_add_u32 v1, v9, 2, v8
	v_mov_b32_e32 v2, v9
	ds_read_b32 v4, v1
	ds_read_b32 v5, v1 offset:528
	ds_read_b32 v6, v1 offset:1056
	ds_read_b32 v7, v1 offset:1584
	s_waitcnt lgkmcnt(0)
	v_lshl_or_b32 v4, v5, 1, v4
	v_lshl_or_b32 v4, v6, 2, v4
	v_lshl_or_b32 v4, v7, 3, v4
	v_cmp_ne_u32_e64 s[10:11], 0, v4
	s_nop 1
	v_mbcnt_lo_u32_b32 v5, s10, 0
	v_mbcnt_hi_u32_b32 v5, s11, v5
	v_add_u32_e32 v5, s7, v5
	v_lshlrev_b32_e32 v5, 2, v5
	v_add_u32_e32 v5, 0x19100, v5
	s_bcnt1_i32_b64 s2, s[10:11]
	s_add_i32 s7, s7, s2
	s_and_b64 exec, exec, s[10:11]
	ds_write_b32 v5, v2
	ds_write_b32 v5, v4 offset:512
	s_mov_b64 exec, s[0:1]
	v_add_u32_e32 v2, 64, v9
	v_lshl_add_u32 v1, v2, 2, v8
	ds_read_b32 v4, v1
	ds_read_b32 v5, v1 offset:528
	ds_read_b32 v6, v1 offset:1056
	ds_read_b32 v7, v1 offset:1584
	s_waitcnt lgkmcnt(0)
	v_lshl_or_b32 v4, v5, 1, v4
	v_lshl_or_b32 v4, v6, 2, v4
	v_lshl_or_b32 v4, v7, 3, v4
	v_cmp_ne_u32_e64 s[10:11], 0, v4
	s_nop 1
	v_mbcnt_lo_u32_b32 v5, s10, 0
	v_mbcnt_hi_u32_b32 v5, s11, v5
	v_add_u32_e32 v5, s7, v5
	v_lshlrev_b32_e32 v5, 2, v5
	v_add_u32_e32 v5, 0x19100, v5
	s_bcnt1_i32_b64 s2, s[10:11]
	s_add_i32 s7, s7, s2
	s_and_b64 exec, exec, s[10:11]
	ds_write_b32 v5, v2
	ds_write_b32 v5, v4 offset:512
	s_mov_b64 exec, s[0:1]
	v_add_u32_e32 v2, 128, v9
	v_lshl_add_u32 v1, v2, 2, v8
	v_cmp_gt_u32_e32 vcc, 129, v2
	s_and_b64 exec, exec, vcc
	ds_read_b32 v4, v1
	ds_read_b32 v5, v1 offset:528
	ds_read_b32 v6, v1 offset:1056
	ds_read_b32 v7, v1 offset:1584
	s_waitcnt lgkmcnt(0)
	v_lshl_or_b32 v4, v5, 1, v4
	v_lshl_or_b32 v4, v6, 2, v4
	v_lshl_or_b32 v4, v7, 3, v4
	v_cmp_ne_u32_e64 s[10:11], 0, v4
	s_nop 1
	v_mbcnt_lo_u32_b32 v5, s10, 0
	v_mbcnt_hi_u32_b32 v5, s11, v5
	v_add_u32_e32 v5, s7, v5
	v_lshlrev_b32_e32 v5, 2, v5
	v_add_u32_e32 v5, 0x19100, v5
	s_bcnt1_i32_b64 s2, s[10:11]
	s_add_i32 s7, s7, s2
	s_and_b64 exec, exec, s[10:11]
	ds_write_b32 v5, v2
	ds_write_b32 v5, v4 offset:512
	s_mov_b64 exec, s[0:1]
	v_mov_b32_e32 v1, 0x19500
	v_mov_b32_e32 v2, s7
	ds_write_b32 v1, v2
	v_lshlrev_b32_e32 v1, 2, v9
	v_add_u32_e32 v1, 0x22800, v1
	s_waitcnt vmcnt(0)
	ds_write_b32 v1, v16

; __device__ __forceinline__ void attn_item(const P& p, Frame& F, const bool is_s, const int b, const int g, const int c) {
;     ...
;                 if (loader && i + 1 < ntiles) { const void* kp1; const void* vp1; int pitch1, nv1; bool f1; SAMPLE_TILE(i + 1, kp1, vp1, pitch1, f1, nv1); loader_stage(F, kp1, vp1, pitch1, f1, nv1, tid - 256, ((i + 1) & 1) * A_BUF2); }
.LBB0_2084:
	s_mov_b64 s[6:7], 0x200
	s_andn2_b64 vcc, exec, s[10:11]
	s_waitcnt vmcnt(2)
	v_mov_b64_e32 v[10:11], s[70:71]
	v_mov_b64_e32 v[4:5], s[80:81]
	s_cbranch_vccnz .LBB0_2090
	s_lshl_b32 s6, s26, 2
	s_add_i32 s6, s6, 0
	s_add_i32 s6, s6, 0x19100
	v_mov_b32_e32 v2, s6
	ds_read_b32 v2, v2
	s_movk_i32 s6, 0x7f
	s_waitcnt lgkmcnt(0)
	v_cmp_lt_i32_e32 vcc, s6, v2
	s_cbranch_vccnz .LBB0_2088
	v_ashrrev_i32_e32 v4, 1, v2
	v_lshlrev_b32_e32 v4, 2, v4
	v_add_u32_e32 v4, 0x22800, v4
	s_nop 0
	ds_read_b32 v4, v4
	v_lshlrev_b32_e32 v2, 6, v2
	v_and_b32_e32 v2, 64, v2
	s_mov_b64 s[6:7], 0x800
	s_mov_b32 s27, 64
	s_mov_b64 s[46:47], -1
	s_waitcnt vmcnt(0) lgkmcnt(0)
	v_lshlrev_b32_e32 v4, 7, v4
	v_or_b32_e32 v4, v4, v2
	v_ashrrev_i32_e32 v5, 31, v4
	v_lshlrev_b64 v[4:5], 12, v[4:5]
	v_lshl_add_u64 v[4:5], s[38:39], 0, v[4:5]
	v_lshl_add_u64 v[10:11], v[4:5], 0, s[6:7]
	s_mov_b64 s[6:7], 0xc00
	v_lshl_add_u64 v[4:5], v[4:5], 0, s[6:7]
	s_branch .LBB0_2089
